# LRU: -log2e folded into the gate biases (v_fmamk) and log2e into log-sigmoid(lambda): 48 VALU fewer per chunk and wave
# baseline (speedup 1.0000x reference)
.LBB0_398:
	s_or_b64 exec, exec, s[60:61]
	s_lshl_b64 s[54:55], s[54:55], 22
	s_lshl_b64 s[54:55], s[54:55], 1
	s_add_u32 s54, s46, s54
	s_addc_u32 s55, s47, s55
	s_add_u32 s54, s54, s81
	s_addc_u32 s55, s55, 0
	s_lshl_b32 s60, s77, 1
	s_add_u32 s54, s54, s60
	s_addc_u32 s55, s55, 0
	v_mov_b32_e32 v97, v77
	v_mov_b32_e32 v101, v77
	v_lshl_add_u64 v[0:1], s[54:55], 0, v[96:97]
	v_mov_b32_e32 v99, v77
	v_lshl_add_u64 v[2:3], s[54:55], 0, v[100:101]
	v_lshl_add_u64 v[0:1], v[0:1], 0, v[98:99]
	v_lshl_add_u64 v[4:5], v[2:3], 0, v[98:99]
	global_load_dwordx4 v[0:3], v[0:1], off
	s_nop 0
	global_load_dwordx4 v[4:7], v[4:5], off
	v_add_u32_e32 v95, v119, v120
	s_waitcnt vmcnt(4)
	ds_write_b128 v95, v[12:15]
	s_waitcnt vmcnt(3)
	ds_write_b128 v195, v[16:19]
	s_waitcnt vmcnt(2)
	ds_write_b128 v196, v[20:23]
	s_and_saveexec_b64 s[60:61], s[8:9]
	ds_write_b128 v197, v[8:11]
	s_or_b64 exec, exec, s[60:61]
	s_and_saveexec_b64 s[60:61], s[12:13]
	ds_write_b128 v198, v[24:27]
	s_or_b64 exec, exec, s[60:61]
	v_mul_f32_e64 v8, |v31|, s51
	v_rndne_f32_e32 v9, v8
	v_sub_f32_e32 v10, v8, v9
	v_fma_f32 v8, |v31|, s51, -v8
	v_fma_f32 v8, |v31|, s64, v8
	v_add_f32_e32 v8, v10, v8
	v_exp_f32_e32 v8, v8
	v_cvt_i32_f32_e32 v9, v9
	v_cmp_ngt_f32_e64 vcc, |v31|, s65
	v_max_f32_e64 v10, -v31, -v31
	v_max_f32_e32 v10, 0, v10
	v_ldexp_f32 v8, v8, v9
	v_cndmask_b32_e32 v8, 0, v8, vcc
	v_cmp_nlt_f32_e64 vcc, |v31|, s66
	s_add_i32 s63, s63, s62
	v_mov_b32_e32 v99, v77
	v_cndmask_b32_e32 v11, v199, v8, vcc
	v_add_f32_e32 v12, 1.0, v11
	v_add_f32_e32 v8, -1.0, v12
	v_sub_f32_e32 v9, v8, v12
	v_add_f32_e32 v9, 1.0, v9
	v_sub_f32_e32 v8, v11, v8
	v_add_f32_e32 v13, v8, v9
	v_frexp_mant_f32_e32 v14, v12
	v_cvt_f64_f32_e32 v[8:9], v12
	v_frexp_exp_i32_f64_e32 v8, v[8:9]
	v_cmp_gt_f32_e32 vcc, s68, v14
	s_cmp_eq_u32 s80, 0
	v_mov_b32_e32 v104, 0
	v_subbrev_co_u32_e32 v8, vcc, 0, v8, vcc
	v_sub_u32_e32 v9, 0, v8
	v_ldexp_f32 v12, v12, v9
	v_ldexp_f32 v9, v13, v9
	v_add_f32_e32 v13, -1.0, v12
	v_add_f32_e32 v16, 1.0, v12
	v_add_f32_e32 v14, 1.0, v13
	v_add_f32_e32 v17, -1.0, v16
	v_sub_f32_e32 v14, v12, v14
	v_sub_f32_e32 v12, v12, v17
	v_add_f32_e32 v14, v9, v14
	v_add_f32_e32 v9, v9, v12
	v_add_f32_e32 v12, v16, v9
	v_rcp_f32_e32 v17, v12
	v_add_f32_e32 v15, v13, v14
	v_sub_f32_e32 v13, v13, v15
	v_add_f32_e32 v13, v14, v13
	v_sub_f32_e32 v14, v16, v12
	v_add_f32_e32 v9, v9, v14
	v_mul_f32_e32 v14, v15, v17
	v_mul_f32_e32 v16, v12, v14
	v_fma_f32 v18, v14, v12, -v16
	v_fmac_f32_e32 v18, v14, v9
	v_add_f32_e32 v19, v16, v18
	v_sub_f32_e32 v20, v15, v19
	v_sub_f32_e32 v15, v15, v20
	v_sub_f32_e32 v16, v19, v16
	v_sub_f32_e32 v15, v15, v19
	v_add_f32_e32 v13, v13, v15
	v_sub_f32_e32 v15, v16, v18
	v_add_f32_e32 v13, v15, v13
	v_add_f32_e32 v15, v20, v13
	v_mul_f32_e32 v16, v17, v15
	v_mul_f32_e32 v18, v12, v16
	v_fma_f32 v12, v16, v12, -v18
	v_fmac_f32_e32 v12, v16, v9
	v_sub_f32_e32 v9, v20, v15
	v_add_f32_e32 v9, v13, v9
	v_add_f32_e32 v13, v18, v12
	v_sub_f32_e32 v19, v15, v13
	v_sub_f32_e32 v15, v15, v19
	v_sub_f32_e32 v18, v13, v18
	v_sub_f32_e32 v13, v15, v13
	v_add_f32_e32 v9, v9, v13
	v_sub_f32_e32 v12, v18, v12
	v_cvt_f32_i32_e32 v8, v8
	v_add_f32_e32 v9, v12, v9
	v_add_f32_e32 v12, v14, v16
	v_add_f32_e32 v9, v19, v9
	v_sub_f32_e32 v13, v12, v14
	v_mul_f32_e32 v9, v17, v9
	v_sub_f32_e32 v13, v16, v13
	v_add_f32_e32 v9, v13, v9
	v_mul_f32_e32 v16, 0x3f317218, v8
	v_add_f32_e32 v13, v12, v9
	v_fma_f32 v17, v8, s69, -v16
	v_mul_f32_e32 v14, v13, v13
	v_fmac_f32_e32 v17, 0xb102e308, v8
	v_sub_f32_e32 v8, v13, v12
	v_fmamk_f32 v15, v14, 0x3e9b6dac, v186
	v_sub_f32_e32 v8, v9, v8
	v_add_f32_e32 v9, v16, v17
	v_fmaak_f32 v15, v14, v15, 0x3f2aaada
	v_sub_f32_e32 v12, v9, v16
	v_ldexp_f32 v16, v13, 1
	v_mul_f32_e32 v13, v13, v14
	v_mul_f32_e32 v13, v13, v15
	v_add_f32_e32 v14, v16, v13
	v_sub_f32_e32 v15, v14, v16
	v_ldexp_f32 v8, v8, 1
	v_sub_f32_e32 v13, v13, v15
	v_add_f32_e32 v8, v8, v13
	v_add_f32_e32 v13, v14, v8
	v_sub_f32_e32 v14, v13, v14
	v_sub_f32_e32 v8, v8, v14
	v_add_f32_e32 v14, v9, v13
	v_sub_f32_e32 v15, v14, v9
	v_sub_f32_e32 v16, v14, v15
	v_sub_f32_e32 v12, v17, v12
	v_sub_f32_e32 v9, v9, v16
	v_sub_f32_e32 v13, v13, v15
	v_add_f32_e32 v9, v13, v9
	v_add_f32_e32 v13, v12, v8
	v_sub_f32_e32 v15, v13, v12
	v_sub_f32_e32 v16, v13, v15
	v_sub_f32_e32 v12, v12, v16
	v_sub_f32_e32 v8, v8, v15
	v_add_f32_e32 v9, v13, v9
	v_add_f32_e32 v8, v8, v12
	v_add_f32_e32 v12, v14, v9
	v_sub_f32_e32 v13, v12, v14
	v_sub_f32_e32 v9, v9, v13
	v_add_f32_e32 v8, v8, v9
	v_add_f32_e32 v8, v12, v8
	v_cmp_neq_f32_e32 vcc, s67, v11
	v_mul_f32_e64 v9, |v30|, s51
	s_waitcnt vmcnt(1)
	ds_write_b128 v123, v[0:3]
	s_waitcnt vmcnt(0)
	ds_write_b128 v124, v[4:7]
	v_cndmask_b32_e32 v8, v199, v8, vcc
	v_cmp_lt_f32_e64 vcc, |v11|, s72
	v_lshl_add_u64 v[106:107], s[54:55], 0, v[98:99]
	s_cselect_b64 s[54:55], -1, 0
	v_cndmask_b32_e32 v8, v8, v11, vcc
	v_add_f32_e32 v8, v10, v8
	v_rndne_f32_e32 v10, v9
	v_sub_f32_e32 v11, v9, v10
	v_fma_f32 v9, |v30|, s51, -v9
	v_fma_f32 v9, |v30|, s64, v9
	v_add_f32_e32 v9, v11, v9
	v_exp_f32_e32 v9, v9
	v_cvt_i32_f32_e32 v10, v10
	v_mul_f32_e32 v97, 0xc138aa3b, v8
	v_max_f32_e64 v8, -v30, -v30
	v_max_f32_e32 v11, 0, v8
	v_ldexp_f32 v8, v9, v10
	v_cmp_ngt_f32_e64 vcc, |v30|, s65
	s_cmp_lg_u32 s80, 0
	v_mov_b32_e32 v1, s41
	v_cndmask_b32_e32 v8, 0, v8, vcc
	v_cmp_nlt_f32_e64 vcc, |v30|, s66
	s_mov_b32 s77, 0
	s_cselect_b64 s[60:61], -1, 0
	v_cndmask_b32_e32 v10, v199, v8, vcc
	v_add_f32_e32 v12, 1.0, v10
	v_add_f32_e32 v8, -1.0, v12
	v_sub_f32_e32 v9, v8, v12
	v_add_f32_e32 v9, 1.0, v9
	v_sub_f32_e32 v8, v10, v8
	v_add_f32_e32 v13, v8, v9
	v_frexp_mant_f32_e32 v14, v12
	v_cvt_f64_f32_e32 v[8:9], v12
	v_frexp_exp_i32_f64_e32 v8, v[8:9]
	v_cmp_gt_f32_e32 vcc, s68, v14
	s_movk_i32 s80, 0x80
	v_mov_b32_e32 v105, v104
	v_subbrev_co_u32_e32 v8, vcc, 0, v8, vcc
	v_sub_u32_e32 v9, 0, v8
	v_ldexp_f32 v12, v12, v9
	v_ldexp_f32 v9, v13, v9
	v_add_f32_e32 v13, -1.0, v12
	v_add_f32_e32 v16, 1.0, v12
	v_add_f32_e32 v14, 1.0, v13
	v_add_f32_e32 v17, -1.0, v16
	v_sub_f32_e32 v14, v12, v14
	v_sub_f32_e32 v12, v12, v17
	v_add_f32_e32 v14, v9, v14
	v_add_f32_e32 v9, v9, v12
	v_add_f32_e32 v12, v16, v9
	v_rcp_f32_e32 v17, v12
	v_add_f32_e32 v15, v13, v14
	v_sub_f32_e32 v13, v13, v15
	v_add_f32_e32 v13, v14, v13
	v_sub_f32_e32 v14, v16, v12
	v_add_f32_e32 v9, v9, v14
	v_mul_f32_e32 v14, v15, v17
	v_mul_f32_e32 v16, v12, v14
	v_fma_f32 v18, v14, v12, -v16
	v_fmac_f32_e32 v18, v14, v9
	v_add_f32_e32 v19, v16, v18
	v_sub_f32_e32 v20, v15, v19
	v_sub_f32_e32 v15, v15, v20
	v_sub_f32_e32 v16, v19, v16
	v_sub_f32_e32 v15, v15, v19
	v_add_f32_e32 v13, v13, v15
	v_sub_f32_e32 v15, v16, v18
	v_add_f32_e32 v13, v15, v13
	v_add_f32_e32 v15, v20, v13
	v_mul_f32_e32 v16, v17, v15
	v_mul_f32_e32 v18, v12, v16
	v_fma_f32 v12, v16, v12, -v18
	v_fmac_f32_e32 v12, v16, v9
	v_sub_f32_e32 v9, v20, v15
	v_add_f32_e32 v9, v13, v9
	v_add_f32_e32 v13, v18, v12
	v_sub_f32_e32 v19, v15, v13
	v_sub_f32_e32 v15, v15, v19
	v_sub_f32_e32 v18, v13, v18
	v_sub_f32_e32 v13, v15, v13
	v_add_f32_e32 v9, v9, v13
	v_sub_f32_e32 v12, v18, v12
	v_cvt_f32_i32_e32 v8, v8
	v_add_f32_e32 v9, v12, v9
	v_add_f32_e32 v12, v14, v16
	v_add_f32_e32 v9, v19, v9
	v_sub_f32_e32 v13, v12, v14
	v_mul_f32_e32 v9, v17, v9
	v_sub_f32_e32 v13, v16, v13
	v_add_f32_e32 v9, v13, v9
	v_mul_f32_e32 v16, 0x3f317218, v8
	v_add_f32_e32 v13, v12, v9
	v_fma_f32 v17, v8, s69, -v16
	v_mul_f32_e32 v14, v13, v13
	v_fmac_f32_e32 v17, 0xb102e308, v8
	v_sub_f32_e32 v8, v13, v12
	v_fmamk_f32 v15, v14, 0x3e9b6dac, v186
	v_sub_f32_e32 v8, v9, v8
	v_add_f32_e32 v9, v16, v17
	v_fmaak_f32 v15, v14, v15, 0x3f2aaada
	v_sub_f32_e32 v12, v9, v16
	v_ldexp_f32 v16, v13, 1
	v_mul_f32_e32 v13, v13, v14
	v_mul_f32_e32 v13, v13, v15
	v_add_f32_e32 v14, v16, v13
	v_sub_f32_e32 v15, v14, v16
	v_ldexp_f32 v8, v8, 1
	v_sub_f32_e32 v13, v13, v15
	v_add_f32_e32 v8, v8, v13
	v_add_f32_e32 v13, v14, v8
	v_sub_f32_e32 v14, v13, v14
	v_sub_f32_e32 v8, v8, v14
	v_add_f32_e32 v14, v9, v13
	v_sub_f32_e32 v15, v14, v9
	v_sub_f32_e32 v16, v14, v15
	v_sub_f32_e32 v12, v17, v12
	v_sub_f32_e32 v9, v9, v16
	v_sub_f32_e32 v13, v13, v15
	v_add_f32_e32 v9, v13, v9
	v_add_f32_e32 v13, v12, v8
	v_sub_f32_e32 v15, v13, v12
	v_sub_f32_e32 v16, v13, v15
	v_sub_f32_e32 v12, v12, v16
	v_sub_f32_e32 v8, v8, v15
	v_add_f32_e32 v9, v13, v9
	v_add_f32_e32 v8, v8, v12
	v_add_f32_e32 v12, v14, v9
	v_sub_f32_e32 v13, v12, v14
	v_sub_f32_e32 v9, v9, v13
	v_add_f32_e32 v8, v8, v9
	v_add_f32_e32 v8, v12, v8
	v_cmp_neq_f32_e32 vcc, s67, v10
	v_mul_f32_e64 v9, |v29|, s51
	v_mov_b32_e32 v110, v104
	v_cndmask_b32_e32 v8, v199, v8, vcc
	v_cmp_lt_f32_e64 vcc, |v10|, s72
	v_mov_b32_e32 v111, v104
	s_waitcnt lgkmcnt(0)
	v_cndmask_b32_e32 v8, v8, v10, vcc
	v_rndne_f32_e32 v10, v9
	v_add_f32_e32 v8, v11, v8
	v_sub_f32_e32 v11, v9, v10
	v_fma_f32 v9, |v29|, s51, -v9
	v_fma_f32 v9, |v29|, s64, v9
	v_add_f32_e32 v9, v11, v9
	v_exp_f32_e32 v9, v9
	v_cvt_i32_f32_e32 v10, v10
	v_mul_f32_e32 v101, 0xc138aa3b, v8
	v_max_f32_e64 v8, -v29, -v29
	v_max_f32_e32 v11, 0, v8
	v_ldexp_f32 v8, v9, v10
	v_cmp_ngt_f32_e64 vcc, |v29|, s65
	s_barrier
	s_nop 0
	v_cndmask_b32_e32 v8, 0, v8, vcc
	v_cmp_nlt_f32_e64 vcc, |v29|, s66
	s_nop 1
	v_cndmask_b32_e32 v10, v199, v8, vcc
	v_add_f32_e32 v12, 1.0, v10
	v_add_f32_e32 v8, -1.0, v12
	v_sub_f32_e32 v9, v8, v12
	v_add_f32_e32 v9, 1.0, v9
	v_sub_f32_e32 v8, v10, v8
	v_add_f32_e32 v13, v8, v9
	v_frexp_mant_f32_e32 v14, v12
	v_cvt_f64_f32_e32 v[8:9], v12
	v_frexp_exp_i32_f64_e32 v8, v[8:9]
	v_cmp_gt_f32_e32 vcc, s68, v14
	s_nop 1
	v_subbrev_co_u32_e32 v8, vcc, 0, v8, vcc
	v_sub_u32_e32 v9, 0, v8
	v_ldexp_f32 v12, v12, v9
	v_ldexp_f32 v9, v13, v9
	v_add_f32_e32 v13, -1.0, v12
	v_add_f32_e32 v16, 1.0, v12
	v_add_f32_e32 v14, 1.0, v13
	v_add_f32_e32 v17, -1.0, v16
	v_sub_f32_e32 v14, v12, v14
	v_sub_f32_e32 v12, v12, v17
	v_add_f32_e32 v14, v9, v14
	v_add_f32_e32 v9, v9, v12
	v_add_f32_e32 v12, v16, v9
	v_rcp_f32_e32 v17, v12
	v_add_f32_e32 v15, v13, v14
	v_sub_f32_e32 v13, v13, v15
	v_add_f32_e32 v13, v14, v13
	v_sub_f32_e32 v14, v16, v12
	v_add_f32_e32 v9, v9, v14
	v_mul_f32_e32 v14, v15, v17
	v_mul_f32_e32 v16, v12, v14
	v_fma_f32 v18, v14, v12, -v16
	v_fmac_f32_e32 v18, v14, v9
	v_add_f32_e32 v19, v16, v18
	v_sub_f32_e32 v20, v15, v19
	v_sub_f32_e32 v15, v15, v20
	v_sub_f32_e32 v16, v19, v16
	v_sub_f32_e32 v15, v15, v19
	v_add_f32_e32 v13, v13, v15
	v_sub_f32_e32 v15, v16, v18
	v_add_f32_e32 v13, v15, v13
	v_add_f32_e32 v15, v20, v13
	v_mul_f32_e32 v16, v17, v15
	v_mul_f32_e32 v18, v12, v16
	v_fma_f32 v12, v16, v12, -v18
	v_fmac_f32_e32 v12, v16, v9
	v_sub_f32_e32 v9, v20, v15
	v_add_f32_e32 v9, v13, v9
	v_add_f32_e32 v13, v18, v12
	v_sub_f32_e32 v19, v15, v13
	v_sub_f32_e32 v15, v15, v19
	v_sub_f32_e32 v18, v13, v18
	v_sub_f32_e32 v13, v15, v13
	v_add_f32_e32 v9, v9, v13
	v_sub_f32_e32 v12, v18, v12
	v_cvt_f32_i32_e32 v8, v8
	v_add_f32_e32 v9, v12, v9
	v_add_f32_e32 v12, v14, v16
	v_add_f32_e32 v9, v19, v9
	v_sub_f32_e32 v13, v12, v14
	v_mul_f32_e32 v9, v17, v9
	v_sub_f32_e32 v13, v16, v13
	v_add_f32_e32 v9, v13, v9
	v_mul_f32_e32 v16, 0x3f317218, v8
	v_add_f32_e32 v13, v12, v9
	v_fma_f32 v17, v8, s69, -v16
	v_mul_f32_e32 v14, v13, v13
	v_fmac_f32_e32 v17, 0xb102e308, v8
	v_sub_f32_e32 v8, v13, v12
	v_fmamk_f32 v15, v14, 0x3e9b6dac, v186
	v_sub_f32_e32 v8, v9, v8
	v_add_f32_e32 v9, v16, v17
	v_fmaak_f32 v15, v14, v15, 0x3f2aaada
	v_sub_f32_e32 v12, v9, v16
	v_ldexp_f32 v16, v13, 1
	v_mul_f32_e32 v13, v13, v14
	v_mul_f32_e32 v13, v13, v15
	v_add_f32_e32 v14, v16, v13
	v_sub_f32_e32 v15, v14, v16
	v_ldexp_f32 v8, v8, 1
	v_sub_f32_e32 v13, v13, v15
	v_add_f32_e32 v8, v8, v13
	v_add_f32_e32 v13, v14, v8
	v_sub_f32_e32 v14, v13, v14
	v_sub_f32_e32 v8, v8, v14
	v_add_f32_e32 v14, v9, v13
	v_sub_f32_e32 v15, v14, v9
	v_sub_f32_e32 v16, v14, v15
	v_sub_f32_e32 v12, v17, v12
	v_sub_f32_e32 v9, v9, v16
	v_sub_f32_e32 v13, v13, v15
	v_add_f32_e32 v9, v13, v9
	v_add_f32_e32 v13, v12, v8
	v_sub_f32_e32 v15, v13, v12
	v_sub_f32_e32 v16, v13, v15
	v_sub_f32_e32 v12, v12, v16
	v_sub_f32_e32 v8, v8, v15
	v_add_f32_e32 v9, v13, v9
	v_add_f32_e32 v8, v8, v12
	v_add_f32_e32 v12, v14, v9
	v_sub_f32_e32 v13, v12, v14
	v_sub_f32_e32 v9, v9, v13
	v_add_f32_e32 v8, v8, v9
	v_add_f32_e32 v8, v12, v8
	v_cmp_neq_f32_e32 vcc, s67, v10
	v_mul_f32_e64 v9, |v28|, s51
	s_nop 0
	v_cndmask_b32_e32 v8, v199, v8, vcc
	v_cmp_lt_f32_e64 vcc, |v10|, s72
	s_nop 1
	v_cndmask_b32_e32 v8, v8, v10, vcc
	v_rndne_f32_e32 v10, v9
	v_add_f32_e32 v8, v11, v8
	v_sub_f32_e32 v11, v9, v10
	v_fma_f32 v9, |v28|, s51, -v9
	v_fma_f32 v9, |v28|, s64, v9
	v_add_f32_e32 v9, v11, v9
	v_exp_f32_e32 v9, v9
	v_cvt_i32_f32_e32 v10, v10
	v_mul_f32_e32 v210, 0xc138aa3b, v8
	v_max_f32_e64 v8, -v28, -v28
	v_max_f32_e32 v11, 0, v8
	v_ldexp_f32 v8, v9, v10
	v_cmp_ngt_f32_e64 vcc, |v28|, s65
	s_nop 1
	v_cndmask_b32_e32 v8, 0, v8, vcc
	v_cmp_nlt_f32_e64 vcc, |v28|, s66
	s_nop 1
	v_cndmask_b32_e32 v10, v199, v8, vcc
	v_add_f32_e32 v12, 1.0, v10
	v_add_f32_e32 v8, -1.0, v12
	v_sub_f32_e32 v9, v8, v12
	v_add_f32_e32 v9, 1.0, v9
	v_sub_f32_e32 v8, v10, v8
	v_add_f32_e32 v13, v8, v9
	v_frexp_mant_f32_e32 v14, v12
	v_cvt_f64_f32_e32 v[8:9], v12
	v_frexp_exp_i32_f64_e32 v8, v[8:9]
	v_cmp_gt_f32_e32 vcc, s68, v14
	s_nop 1
	v_subbrev_co_u32_e32 v8, vcc, 0, v8, vcc
	v_sub_u32_e32 v9, 0, v8
	v_ldexp_f32 v12, v12, v9
	v_ldexp_f32 v9, v13, v9
	v_add_f32_e32 v13, -1.0, v12
	v_add_f32_e32 v16, 1.0, v12
	v_add_f32_e32 v14, 1.0, v13
	v_add_f32_e32 v17, -1.0, v16
	v_sub_f32_e32 v14, v12, v14
	v_sub_f32_e32 v12, v12, v17
	v_add_f32_e32 v14, v9, v14
	v_add_f32_e32 v9, v9, v12
	v_add_f32_e32 v12, v16, v9
	v_rcp_f32_e32 v17, v12
	v_add_f32_e32 v15, v13, v14
	v_sub_f32_e32 v13, v13, v15
	v_add_f32_e32 v13, v14, v13
	v_sub_f32_e32 v14, v16, v12
	v_add_f32_e32 v9, v9, v14
	v_mul_f32_e32 v14, v15, v17
	v_mul_f32_e32 v16, v12, v14
	v_fma_f32 v18, v14, v12, -v16
	v_fmac_f32_e32 v18, v14, v9
	v_add_f32_e32 v19, v16, v18
	v_sub_f32_e32 v20, v15, v19
	v_sub_f32_e32 v15, v15, v20
	v_sub_f32_e32 v16, v19, v16
	v_sub_f32_e32 v15, v15, v19
	v_add_f32_e32 v13, v13, v15
	v_sub_f32_e32 v15, v16, v18
	v_add_f32_e32 v13, v15, v13
	v_add_f32_e32 v15, v20, v13
	v_mul_f32_e32 v16, v17, v15
	v_mul_f32_e32 v18, v12, v16
	v_fma_f32 v12, v16, v12, -v18
	v_fmac_f32_e32 v12, v16, v9
	v_sub_f32_e32 v9, v20, v15
	v_add_f32_e32 v9, v13, v9
	v_add_f32_e32 v13, v18, v12
	v_sub_f32_e32 v19, v15, v13
	v_sub_f32_e32 v15, v15, v19
	v_sub_f32_e32 v18, v13, v18
	v_sub_f32_e32 v13, v15, v13
	v_add_f32_e32 v9, v9, v13
	v_sub_f32_e32 v12, v18, v12
	v_cvt_f32_i32_e32 v8, v8
	v_add_f32_e32 v9, v12, v9
	v_add_f32_e32 v12, v14, v16
	v_add_f32_e32 v9, v19, v9
	v_sub_f32_e32 v13, v12, v14
	v_mul_f32_e32 v9, v17, v9
	v_sub_f32_e32 v13, v16, v13
	v_add_f32_e32 v9, v13, v9
	v_mul_f32_e32 v16, 0x3f317218, v8
	v_add_f32_e32 v13, v12, v9
	v_fma_f32 v17, v8, s69, -v16
	v_mul_f32_e32 v14, v13, v13
	v_fmac_f32_e32 v17, 0xb102e308, v8
	v_sub_f32_e32 v8, v13, v12
	v_fmamk_f32 v15, v14, 0x3e9b6dac, v186
	v_sub_f32_e32 v8, v9, v8
	v_add_f32_e32 v9, v16, v17
	v_fmaak_f32 v15, v14, v15, 0x3f2aaada
	v_sub_f32_e32 v12, v9, v16
	v_ldexp_f32 v16, v13, 1
	v_mul_f32_e32 v13, v13, v14
	v_mul_f32_e32 v13, v13, v15
	v_add_f32_e32 v14, v16, v13
	v_sub_f32_e32 v15, v14, v16
	v_ldexp_f32 v8, v8, 1
	v_sub_f32_e32 v13, v13, v15
	v_add_f32_e32 v8, v8, v13
	v_add_f32_e32 v13, v14, v8
	v_sub_f32_e32 v14, v13, v14
	v_sub_f32_e32 v8, v8, v14
	v_add_f32_e32 v14, v9, v13
	v_sub_f32_e32 v15, v14, v9
	v_sub_f32_e32 v16, v14, v15
	v_sub_f32_e32 v12, v17, v12
	v_sub_f32_e32 v9, v9, v16
	v_sub_f32_e32 v13, v13, v15
	v_add_f32_e32 v9, v13, v9
	v_add_f32_e32 v13, v12, v8
	v_sub_f32_e32 v15, v13, v12
	v_sub_f32_e32 v16, v13, v15
	v_sub_f32_e32 v12, v12, v16
	v_sub_f32_e32 v8, v8, v15
	v_add_f32_e32 v9, v13, v9
	v_add_f32_e32 v8, v8, v12
	v_add_f32_e32 v12, v14, v9
	v_sub_f32_e32 v13, v12, v14
	v_sub_f32_e32 v9, v9, v13
	v_add_f32_e32 v8, v8, v9
	v_add_f32_e32 v8, v12, v8
	v_cmp_neq_f32_e32 vcc, s67, v10
	s_nop 1
	v_cndmask_b32_e32 v8, v199, v8, vcc
	v_cmp_lt_f32_e64 vcc, |v10|, s72
	s_nop 1
	v_cndmask_b32_e32 v8, v8, v10, vcc
	v_add_f32_e32 v8, v11, v8
	v_mul_f32_e32 v211, 0xc138aa3b, v8
	v_add_u32_e32 v8, s63, v146
	v_lshl_or_b32 v0, v8, 1, s40
	v_lshl_add_u64 v[108:109], v[92:93], 0, v[0:1]
	s_mov_b64 s[62:63], 0
	v_mul_f32_e32 v202, 0xbfb8aa3b, v202
	v_mul_f32_e32 v203, 0xbfb8aa3b, v203
	v_mul_f32_e32 v204, 0xbfb8aa3b, v204
	v_mul_f32_e32 v205, 0xbfb8aa3b, v205
	v_mul_f32_e32 v206, 0xbfb8aa3b, v206
	v_mul_f32_e32 v207, 0xbfb8aa3b, v207
	v_mul_f32_e32 v208, 0xbfb8aa3b, v208
	v_mul_f32_e32 v209, 0xbfb8aa3b, v209
	s_branch .LBB0_404

.LBB0_422:
	v_cvt_pk_bf16_f32 v216, v44, v45
	v_cvt_pk_bf16_f32 v217, v46, v47
	v_cvt_pk_bf16_f32 v218, v48, v49
	v_cvt_pk_bf16_f32 v219, v50, v51
	ds_read_b128 v[44:47], v128 offset:36032
	ds_read_b128 v[48:51], v128 offset:40384
	s_waitcnt lgkmcnt(1)
	v_mfma_f32_16x16x32_bf16 v[56:59], v[216:219], v[44:47], v[64:67]
	ds_read_b128 v[44:47], v128 offset:53440
	ds_read_b128 v[60:63], v128 offset:57792
	s_waitcnt lgkmcnt(1)
	v_mfma_f32_16x16x32_bf16 v[64:67], v[216:219], v[44:47], v[68:71]
	s_nop 2
	ds_read_b128 v[68:71], v128 offset:44736
	v_mfma_f32_16x16x32_bf16 v[44:47], v[216:219], v[48:51], v[72:75]
	v_fmamk_f32 v56, v56, 0xbfb8aa3b, v202
	v_exp_f32_e32 v56, v56
	s_waitcnt lgkmcnt(1)
	v_mfma_f32_16x16x32_bf16 v[48:51], v[216:219], v[60:63], v[36:39]
	ds_read_b128 v[60:63], v128 offset:62144
	ds_read_b128 v[72:75], v128 offset:49088
	s_waitcnt lgkmcnt(2)
	v_mfma_f32_16x16x32_bf16 v[36:39], v[216:219], v[68:71], v[52:55]
	ds_read_b128 v[68:71], v138 offset:13056
	s_nop 1
	v_add_f32_e32 v52, 1.0, v56
	v_rcp_f32_e32 v52, v52
	v_fmamk_f32 v55, v65, 0xbfb8aa3b, v203
	v_mul_f32_e32 v52, v97, v52
	v_exp_f32_e32 v76, v52
	v_fmamk_f32 v52, v57, 0xbfb8aa3b, v202
	v_exp_f32_e32 v52, v52
	v_fmamk_f32 v53, v64, 0xbfb8aa3b, v203
	s_waitcnt lgkmcnt(2)
	v_mfma_f32_16x16x32_bf16 v[40:43], v[216:219], v[60:63], v[40:43]
	v_exp_f32_e32 v56, v55
	v_add_f32_e32 v52, 1.0, v52
	v_rcp_f32_e32 v52, v52
	v_exp_f32_e32 v53, v53
	v_fma_f32 v54, -v76, v76, 1.0
	v_max_f32_e32 v54, 0, v54
	v_mul_f32_e32 v52, v97, v52
	v_exp_f32_e32 v60, v52
	v_sqrt_f32_e32 v55, v54
	v_add_f32_e32 v52, 1.0, v56
	v_fma_f32 v54, -v60, v60, 1.0
	v_add_f32_e32 v53, 1.0, v53
	v_max_f32_e32 v54, 0, v54
	v_fmamk_f32 v56, v58, 0xbfb8aa3b, v202
	v_rcp_f32_e32 v53, v53
	v_rcp_f32_e32 v52, v52
	v_sqrt_f32_e32 v54, v54
	v_exp_f32_e32 v58, v56
	ds_read2_b32 v[56:57], v201 offset1:68
	v_mul_f32_e32 v99, v60, v76
	v_pk_mul_f32 v[52:53], v[52:53], v[54:55]
	v_add_f32_e32 v54, 1.0, v58
	v_rcp_f32_e32 v61, v54
	s_waitcnt lgkmcnt(0)
	v_mov_b32_e32 v54, v57
	v_fmamk_f32 v55, v66, 0xbfb8aa3b, v203
	v_mul_f32_e32 v57, v97, v61
	v_exp_f32_e32 v61, v57
	v_fmamk_f32 v57, v59, 0xbfb8aa3b, v202
	v_exp_f32_e32 v57, v57
	v_exp_f32_e32 v58, v55
	v_fmamk_f32 v59, v67, 0xbfb8aa3b, v203
	v_add_f32_e32 v57, 1.0, v57
	v_rcp_f32_e32 v57, v57
	v_exp_f32_e32 v62, v59
	v_mov_b32_e32 v55, v56
	v_add_f32_e32 v56, 1.0, v58
	v_mul_f32_e32 v57, v97, v57
	v_exp_f32_e32 v59, v57
	v_rcp_f32_e32 v58, v56
	v_fma_f32 v56, -v61, v61, 1.0
	v_max_f32_e32 v56, 0, v56
	v_sqrt_f32_e32 v64, v56
	v_add_f32_e32 v56, 1.0, v62
	ds_read2_b32 v[62:63], v201 offset0:136 offset1:204
	v_rcp_f32_e32 v65, v56
	v_fma_f32 v56, -v59, v59, 1.0
	v_max_f32_e32 v56, 0, v56
	v_sqrt_f32_e32 v66, v56
	v_pk_mul_f32 v[56:57], v[52:53], v[54:55]
	v_mul_f32_e32 v52, v58, v64
	v_fma_f32 v53, v60, v57, v56
	s_waitcnt lgkmcnt(0)
	v_mov_b32_e32 v60, v62
	v_mul_f32_e32 v54, v53, v61
	v_pk_fma_f32 v[54:55], v[52:53], v[60:61], v[54:55] op_sel_hi:[1,1,0]
	v_mul_f32_e32 v64, v65, v66
	v_mov_b32_e32 v65, v54
	v_mov_b32_e32 v58, v63
	v_mul_f32_e32 v212, v61, v99
	v_pk_mul_f32 v[60:61], v[64:65], v[58:59]
	v_mul_f32_e32 v213, v59, v212
	v_add_f32_e32 v52, v60, v61
	ds_bpermute_b32 v62, v139, v213
	ds_bpermute_b32 v215, v139, v52
	ds_bpermute_b32 v58, v140, v213
	ds_bpermute_b32 v214, v140, v52
	ds_bpermute_b32 v60, v141, v213
	ds_bpermute_b32 v59, v141, v52
	ds_bpermute_b32 v64, v142, v213
	ds_bpermute_b32 v65, v142, v52
	v_mfma_f32_16x16x32_bf16 v[28:31], v[216:219], v[72:75], v[28:31]
	s_waitcnt lgkmcnt(6)
	v_fmac_f32_e32 v215, 0, v62
	v_mfma_f32_16x16x32_bf16 v[32:35], v[216:219], v[68:71], v[32:35]
	s_and_saveexec_b64 s[40:41], s[14:15]
	s_cbranch_execz .LBB0_424
	s_waitcnt lgkmcnt(4)
	v_fma_f32 v55, v215, v58, v214
	s_waitcnt lgkmcnt(3)
	v_mul_f32_e32 v63, v55, v60
	s_waitcnt lgkmcnt(2)
	v_pk_mul_f32 v[66:67], v[62:63], v[58:59]
	v_pk_add_f32 v[68:69], v[62:63], v[58:59]
	s_waitcnt lgkmcnt(1)
	v_mov_b32_e32 v61, v64
	v_mov_b32_e32 v68, v66
	v_pk_mul_f32 v[66:67], v[66:67], v[60:61]
	v_lshl_add_u32 v55, s77, 12, v143
	s_waitcnt lgkmcnt(0)
	v_pk_mul_f32 v[66:67], v[66:67], v[64:65]
	v_pk_fma_f32 v[64:65], v[68:69], v[60:61], v[64:65]
	s_nop 0
	v_mov_b32_e32 v67, v65
	ds_write_b64 v55, v[66:67]
.LBB0_424:
	s_or_b64 exec, exec, s[40:41]
	v_fmamk_f32 v44, v44, 0xbfb8aa3b, v204
	v_exp_f32_e32 v44, v44
	v_fmamk_f32 v48, v48, 0xbfb8aa3b, v205
	v_add_f32_e32 v44, 1.0, v44
	v_rcp_f32_e32 v44, v44
	v_fmamk_f32 v45, v45, 0xbfb8aa3b, v204
	v_exp_f32_e32 v48, v48
	v_exp_f32_e32 v45, v45
	v_mul_f32_e32 v44, v101, v44
	v_exp_f32_e32 v216, v44
	v_add_f32_e32 v44, 1.0, v48
	v_add_f32_e32 v48, 1.0, v45
	v_rcp_f32_e32 v48, v48
	v_fmamk_f32 v49, v49, 0xbfb8aa3b, v205
	v_mul_f32_e32 v48, v101, v48
	v_exp_f32_e32 v56, v48
	v_fmamk_f32 v46, v46, 0xbfb8aa3b, v204
	v_exp_f32_e32 v55, v49
	v_exp_f32_e32 v46, v46
	v_rcp_f32_e32 v45, v44
	v_fma_f32 v44, -v216, v216, 1.0
	v_max_f32_e32 v44, 0, v44
	v_fma_f32 v48, -v56, v56, 1.0
	v_sqrt_f32_e32 v49, v44
	v_add_f32_e32 v44, 1.0, v55
	v_max_f32_e32 v48, 0, v48
	v_add_f32_e32 v46, 1.0, v46
	v_rcp_f32_e32 v44, v44
	v_sqrt_f32_e32 v48, v48
	v_rcp_f32_e32 v46, v46
	s_waitcnt lgkmcnt(0)
	ds_read2_b32 v[64:65], v201 offset0:16 offset1:84
	v_pk_mul_f32 v[44:45], v[44:45], v[48:49]
	v_mul_f32_e32 v46, v101, v46
	v_fmamk_f32 v48, v50, 0xbfb8aa3b, v205
	v_exp_f32_e32 v50, v48
	s_waitcnt lgkmcnt(0)
	v_mov_b32_e32 v48, v65
	v_exp_f32_e32 v65, v46
	v_fmamk_f32 v46, v47, 0xbfb8aa3b, v204
	v_exp_f32_e32 v46, v46
	v_fmamk_f32 v51, v51, 0xbfb8aa3b, v205
	v_exp_f32_e32 v55, v51
	v_add_f32_e32 v50, 1.0, v50
	v_add_f32_e32 v46, 1.0, v46
	v_rcp_f32_e32 v46, v46
	v_rcp_f32_e32 v47, v50
	v_fma_f32 v50, -v65, v65, 1.0
	v_max_f32_e32 v50, 0, v50
	v_mul_f32_e32 v46, v101, v46
	v_exp_f32_e32 v51, v46
	ds_read2_b32 v[66:67], v201 offset0:152 offset1:220
	v_sqrt_f32_e32 v46, v50
	v_add_f32_e32 v50, 1.0, v55
	v_fma_f32 v55, -v51, v51, 1.0
	v_mov_b32_e32 v49, v64
	v_max_f32_e32 v55, 0, v55
	v_rcp_f32_e32 v50, v50
	v_sqrt_f32_e32 v55, v55
	v_pk_mul_f32 v[48:49], v[44:45], v[48:49]
	v_mul_f32_e32 v44, v47, v46
	v_fma_f32 v45, v56, v49, v48
	s_waitcnt lgkmcnt(0)
	v_mov_b32_e32 v64, v66
	v_mul_f32_e32 v46, v45, v65
	v_pk_fma_f32 v[46:47], v[44:45], v[64:65], v[46:47] op_sel_hi:[1,1,0]
	v_mul_f32_e32 v68, v50, v55
	v_mul_f32_e32 v48, v56, v216
	v_mov_b32_e32 v69, v46
	v_mov_b32_e32 v50, v67
	v_mul_f32_e32 v217, v65, v48
	v_pk_mul_f32 v[64:65], v[68:69], v[50:51]
	v_mul_f32_e32 v218, v51, v217
	v_add_f32_e32 v44, v64, v65
	ds_bpermute_b32 v66, v139, v218
	ds_bpermute_b32 v220, v139, v44
	ds_bpermute_b32 v50, v140, v218
	ds_bpermute_b32 v219, v140, v44
	ds_bpermute_b32 v64, v141, v218
	ds_bpermute_b32 v51, v141, v44
	ds_bpermute_b32 v68, v142, v218
	ds_bpermute_b32 v69, v142, v44
	s_waitcnt lgkmcnt(6)
	v_fmac_f32_e32 v220, 0, v66
	s_and_saveexec_b64 s[40:41], s[14:15]
	s_cbranch_execz .LBB0_426
	s_waitcnt lgkmcnt(4)
	v_fma_f32 v47, v220, v50, v219
	s_waitcnt lgkmcnt(3)
	v_mul_f32_e32 v67, v47, v64
	s_waitcnt lgkmcnt(2)
	v_pk_mul_f32 v[70:71], v[66:67], v[50:51]
	v_pk_add_f32 v[72:73], v[66:67], v[50:51]
	s_waitcnt lgkmcnt(1)
	v_mov_b32_e32 v65, v68
	v_mov_b32_e32 v72, v70
	v_pk_mul_f32 v[70:71], v[70:71], v[64:65]
	v_lshl_add_u32 v47, s77, 12, v147
	s_waitcnt lgkmcnt(0)
	v_pk_mul_f32 v[70:71], v[70:71], v[68:69]
	v_pk_fma_f32 v[68:69], v[72:73], v[64:65], v[68:69]
	s_nop 0
	v_mov_b32_e32 v71, v69
	ds_write_b64 v47, v[70:71]
.LBB0_426:
	s_or_b64 exec, exec, s[40:41]
	v_fmamk_f32 v36, v36, 0xbfb8aa3b, v206
	v_exp_f32_e32 v36, v36
	v_fmamk_f32 v40, v40, 0xbfb8aa3b, v207
	v_add_f32_e32 v36, 1.0, v36
	v_rcp_f32_e32 v36, v36
	v_fmamk_f32 v37, v37, 0xbfb8aa3b, v206
	v_exp_f32_e32 v40, v40
	v_exp_f32_e32 v37, v37
	v_mul_f32_e32 v36, v210, v36
	v_exp_f32_e32 v55, v36
	v_add_f32_e32 v36, 1.0, v40
	v_add_f32_e32 v40, 1.0, v37
	v_rcp_f32_e32 v40, v40
	v_fmamk_f32 v41, v41, 0xbfb8aa3b, v207
	v_mul_f32_e32 v40, v210, v40
	v_exp_f32_e32 v56, v40
	v_fmamk_f32 v38, v38, 0xbfb8aa3b, v206
	v_exp_f32_e32 v47, v41
	v_exp_f32_e32 v38, v38
	v_rcp_f32_e32 v37, v36
	v_fma_f32 v36, -v55, v55, 1.0
	v_max_f32_e32 v36, 0, v36
	v_fma_f32 v40, -v56, v56, 1.0
	v_sqrt_f32_e32 v41, v36
	v_add_f32_e32 v36, 1.0, v47
	v_max_f32_e32 v40, 0, v40
	v_add_f32_e32 v38, 1.0, v38
	v_rcp_f32_e32 v36, v36
	v_sqrt_f32_e32 v40, v40
	v_rcp_f32_e32 v38, v38
	s_waitcnt lgkmcnt(0)
	ds_read2_b32 v[68:69], v201 offset0:32 offset1:100
	v_pk_mul_f32 v[36:37], v[36:37], v[40:41]
	v_mul_f32_e32 v38, v210, v38
	v_fmamk_f32 v40, v42, 0xbfb8aa3b, v207
	v_exp_f32_e32 v42, v40
	s_waitcnt lgkmcnt(0)
	v_mov_b32_e32 v40, v69
	v_exp_f32_e32 v69, v38
	v_fmamk_f32 v38, v39, 0xbfb8aa3b, v206
	v_exp_f32_e32 v38, v38
	v_fmamk_f32 v43, v43, 0xbfb8aa3b, v207
	v_exp_f32_e32 v47, v43
	v_add_f32_e32 v42, 1.0, v42
	v_add_f32_e32 v38, 1.0, v38
	v_rcp_f32_e32 v38, v38
	v_rcp_f32_e32 v39, v42
	v_fma_f32 v42, -v69, v69, 1.0
	v_max_f32_e32 v42, 0, v42
	v_mul_f32_e32 v38, v210, v38
	v_exp_f32_e32 v43, v38
	ds_read2_b32 v[70:71], v201 offset0:168 offset1:236
	v_sqrt_f32_e32 v38, v42
	v_add_f32_e32 v42, 1.0, v47
	v_fma_f32 v47, -v43, v43, 1.0
	v_mov_b32_e32 v41, v68
	v_max_f32_e32 v47, 0, v47
	v_rcp_f32_e32 v42, v42
	v_sqrt_f32_e32 v47, v47
	v_pk_mul_f32 v[40:41], v[36:37], v[40:41]
	v_mul_f32_e32 v36, v39, v38
	v_fma_f32 v37, v56, v41, v40
	s_waitcnt lgkmcnt(0)
	v_mov_b32_e32 v68, v70
	v_mul_f32_e32 v38, v37, v69
	v_pk_fma_f32 v[38:39], v[36:37], v[68:69], v[38:39] op_sel_hi:[1,1,0]
	v_mul_f32_e32 v72, v42, v47
	v_mul_f32_e32 v56, v56, v55
	v_mov_b32_e32 v73, v38
	v_mov_b32_e32 v42, v71
	v_mul_f32_e32 v65, v69, v56
	v_pk_mul_f32 v[68:69], v[72:73], v[42:43]
	v_mul_f32_e32 v67, v43, v65
	v_add_f32_e32 v36, v68, v69
	ds_bpermute_b32 v70, v139, v67
	ds_bpermute_b32 v63, v139, v36
	ds_bpermute_b32 v42, v140, v67
	ds_bpermute_b32 v61, v140, v36
	ds_bpermute_b32 v68, v141, v67
	ds_bpermute_b32 v43, v141, v36
	ds_bpermute_b32 v72, v142, v67
	ds_bpermute_b32 v73, v142, v36
	s_waitcnt lgkmcnt(6)
	v_fmac_f32_e32 v63, 0, v70
	s_and_saveexec_b64 s[40:41], s[14:15]
	s_cbranch_execz .LBB0_428
	s_waitcnt lgkmcnt(4)
	v_fma_f32 v39, v63, v42, v61
	s_waitcnt lgkmcnt(3)
	v_mul_f32_e32 v71, v39, v68
	s_waitcnt lgkmcnt(2)
	v_pk_mul_f32 v[74:75], v[70:71], v[42:43]
	v_pk_add_f32 v[112:113], v[70:71], v[42:43]
	s_waitcnt lgkmcnt(1)
	v_mov_b32_e32 v69, v72
	v_mov_b32_e32 v112, v74
	v_pk_mul_f32 v[74:75], v[74:75], v[68:69]
	v_lshl_add_u32 v39, s77, 12, v149
	s_waitcnt lgkmcnt(0)
	v_pk_mul_f32 v[74:75], v[74:75], v[72:73]
	v_pk_fma_f32 v[72:73], v[112:113], v[68:69], v[72:73]
	s_nop 0
	v_mov_b32_e32 v75, v73
	ds_write_b64 v39, v[74:75]
.LBB0_428:
	s_or_b64 exec, exec, s[40:41]
	v_fmamk_f32 v28, v28, 0xbfb8aa3b, v208
	v_exp_f32_e32 v28, v28
	v_fmamk_f32 v32, v32, 0xbfb8aa3b, v209
	v_add_f32_e32 v28, 1.0, v28
	v_rcp_f32_e32 v28, v28
	v_fmamk_f32 v29, v29, 0xbfb8aa3b, v208
	v_exp_f32_e32 v32, v32
	v_exp_f32_e32 v29, v29
	v_mul_f32_e32 v28, v211, v28
	v_exp_f32_e32 v39, v28
	v_add_f32_e32 v28, 1.0, v32
	v_add_f32_e32 v32, 1.0, v29
	v_rcp_f32_e32 v32, v32
	v_fmamk_f32 v33, v33, 0xbfb8aa3b, v209
	v_mul_f32_e32 v32, v211, v32
	v_exp_f32_e32 v47, v32
	v_fmamk_f32 v30, v30, 0xbfb8aa3b, v208
	v_exp_f32_e32 v40, v33
	v_exp_f32_e32 v30, v30
	v_rcp_f32_e32 v29, v28
	v_fma_f32 v28, -v39, v39, 1.0
	v_max_f32_e32 v28, 0, v28
	v_fma_f32 v32, -v47, v47, 1.0
	v_sqrt_f32_e32 v33, v28
	v_add_f32_e32 v28, 1.0, v40
	v_max_f32_e32 v32, 0, v32
	v_add_f32_e32 v30, 1.0, v30
	v_rcp_f32_e32 v28, v28
	v_sqrt_f32_e32 v32, v32
	v_rcp_f32_e32 v30, v30
	s_waitcnt lgkmcnt(0)
	ds_read2_b32 v[72:73], v201 offset0:48 offset1:116
	v_pk_mul_f32 v[28:29], v[28:29], v[32:33]
	v_mul_f32_e32 v30, v211, v30
	v_fmamk_f32 v32, v34, 0xbfb8aa3b, v209
	v_exp_f32_e32 v34, v32
	s_waitcnt lgkmcnt(0)
	v_mov_b32_e32 v32, v73
	v_exp_f32_e32 v73, v30
	v_fmamk_f32 v30, v31, 0xbfb8aa3b, v208
	v_exp_f32_e32 v30, v30
	v_fmamk_f32 v35, v35, 0xbfb8aa3b, v209
	v_exp_f32_e32 v40, v35
	v_add_f32_e32 v34, 1.0, v34
	v_add_f32_e32 v30, 1.0, v30
	v_rcp_f32_e32 v30, v30
	v_rcp_f32_e32 v31, v34
	v_fma_f32 v34, -v73, v73, 1.0
	v_max_f32_e32 v34, 0, v34
	v_mul_f32_e32 v30, v211, v30
	v_exp_f32_e32 v35, v30
	ds_read2_b32 v[74:75], v201 offset0:184 offset1:252
	v_sqrt_f32_e32 v30, v34
	v_add_f32_e32 v34, 1.0, v40
	v_fma_f32 v40, -v35, v35, 1.0
	v_mov_b32_e32 v33, v72
	v_max_f32_e32 v40, 0, v40
	v_rcp_f32_e32 v34, v34
	v_sqrt_f32_e32 v40, v40
	v_pk_mul_f32 v[32:33], v[28:29], v[32:33]
	v_mul_f32_e32 v28, v31, v30
	v_fma_f32 v29, v47, v33, v32
	s_waitcnt lgkmcnt(0)
	v_mov_b32_e32 v72, v74
	v_mul_f32_e32 v30, v29, v73
	v_pk_fma_f32 v[30:31], v[28:29], v[72:73], v[30:31] op_sel_hi:[1,1,0]
	v_mul_f32_e32 v112, v34, v40
	v_mul_f32_e32 v32, v47, v39
	v_mov_b32_e32 v113, v30
	v_mov_b32_e32 v34, v75
	v_mul_f32_e32 v31, v73, v32
	v_pk_mul_f32 v[72:73], v[112:113], v[34:35]
	v_mul_f32_e32 v69, v35, v31
	v_add_f32_e32 v28, v72, v73
	ds_bpermute_b32 v74, v139, v69
	ds_bpermute_b32 v71, v139, v28
	ds_bpermute_b32 v34, v140, v69
	ds_bpermute_b32 v40, v140, v28
	ds_bpermute_b32 v72, v141, v69
	ds_bpermute_b32 v35, v141, v28
	ds_bpermute_b32 v112, v142, v69
	ds_bpermute_b32 v113, v142, v28
	s_and_saveexec_b64 s[40:41], s[16:17]
	s_xor_b64 s[40:41], exec, s[40:41]
	s_lshl_b32 s81, s77, 12
	s_or_saveexec_b64 s[40:41], s[40:41]
	s_waitcnt lgkmcnt(6)
	v_fmac_f32_e32 v71, 0, v74
	v_mov_b32_e32 v47, s81
	s_xor_b64 exec, exec, s[40:41]
	s_cbranch_execz .LBB0_432
	s_waitcnt lgkmcnt(4)
	v_fma_f32 v47, v71, v34, v40
	s_waitcnt lgkmcnt(3)
	v_mul_f32_e32 v75, v47, v72
	s_waitcnt lgkmcnt(2)
	v_pk_mul_f32 v[222:223], v[74:75], v[34:35]
	v_pk_add_f32 v[224:225], v[74:75], v[34:35]
	s_waitcnt lgkmcnt(1)
	v_mov_b32_e32 v73, v112
	v_mov_b32_e32 v224, v222
	v_pk_mul_f32 v[222:223], v[222:223], v[72:73]
	s_lshl_b32 s81, s77, 12
	s_waitcnt lgkmcnt(0)
	v_pk_mul_f32 v[222:223], v[222:223], v[112:113]
	v_pk_fma_f32 v[112:113], v[224:225], v[72:73], v[112:113]
	v_add_u32_e32 v47, s81, v150
	v_mov_b32_e32 v223, v113
	ds_write_b64 v47, v[222:223]
	v_mov_b32_e32 v47, s81
